# v32: v31 + GLA next-chunk V/decay conversions done before the chunk barrier (only LDS writes remain after it)
# baseline (speedup 1.0000x reference)
; #define LAS __attribute__((address_space(3)))
; __device__ __forceinline__ void phase_gla(const Frame& F, int l, int gi, int ng, bool last, unsigned* cw) {
;     ...
;         const int b = item & 7, idx = item >> 3, h = idx >> 2, dir = (idx >> 1) & 1, sl = idx & 1;
;         const float* gwp = (dir ? F.in[17] : F.in[15]) + (size_t)l * 16 * 512 + h * 128;
;         const float* gbp = (dir ? F.in[18] : F.in[16]) + (size_t)l * 512 + h * 128;
;         f16* Oout = dir ? F.OB : F.H16;
;         const int d = tid & 127, tg = tid >> 7;
;         f16x8 gwf;
; #pragma unroll
;         for (int j = 0; j < 8; ++j) gwf[j] = (f16)gwp[(hh * 8 + j) * 512 + (w & 3) * 32 + r32];
;         const float gbv = gbp[(w & 3) * 32 + r32];
;         const int li = tid >> 3, ls = tid & 7;
;         const int vi = tid & 63, vs = tid >> 6;
;         const int it = w >> 2, et = w & 3;
;         const int dt = w >> 1, e2 = (w & 1) * 2;
;         f32x16 Sacc[2];
; #pragma unroll
;         for (int q = 0; q < 2; ++q)
; #pragma unroll
;             for (int e = 0; e < 16; ++e) Sacc[q][e] = 0.f;
;         __syncthreads();
;         for (int i = tid; i < 128 * 136 / 2; i += NTHR) ((LAS unsigned*)(lds + GL_ST))[i] = 0u;
;         u32x4 pq0, pq1, pk0, pk1, pv0, pv1; f32x2 pg;
;         auto chunk_base = [&](int s) -> int { return (s < 4) ? (TL + b * CTXL + (dir ? 3 - s : s) * 64) : (b * SEQ + (dir ? 63 - (s - 4) : (s - 4)) * 64); };
;     ...
;         GLA_LOAD(0);
;         for (int s = 0; s < 68; ++s) {
;             *(LAS u32x4*)(lds + GL_RQ + (li * 136 + ls * 16) * 2) = pq0; *(LAS u32x4*)(lds + GL_RQ + (li * 136 + ls * 16 + 8) * 2) = pq1;
;             *(LAS u32x4*)(lds + GL_RK + (li * 136 + ls * 16) * 2) = pk0; *(LAS u32x4*)(lds + GL_RK + (li * 136 + ls * 16 + 8) * 2) = pk1;
;             *(LAS unsigned*)(lds + GL_LR + (li * 16 + ls * 2) * 2) = pk_f16(pg.x, pg.y);
;             { const f16x8 va = __builtin_bit_cast(f16x8, pv0), vb = __builtin_bit_cast(f16x8, pv1);
; #pragma unroll
;               for (int e = 0; e < 8; e += 2) { const unsigned pa = pk_bf16((float)va[e], (float)va[e + 1]), pb = pk_bf16((float)vb[e], (float)vb[e + 1]);
;                   *(LAS unsigned short*)(lds + GL_VT + ((vs * 16 + e) * 72 + vi) * 2) = (unsigned short)(pa & 0xffffu);
;                   *(LAS unsigned short*)(lds + GL_VT + ((vs * 16 + e + 1) * 72 + vi) * 2) = (unsigned short)(pa >> 16);
.LBB0_642:
	s_or_b64 exec, exec, s[2:3]
	s_mov_b64 s[52:53], s[12:13]
	s_and_b32 s13, s16, 7
	s_bfe_u32 s8, s16, 0x10003
	s_mov_b64 s[54:55], s[30:31]
	s_and_b64 s[2:3], s[84:85], exec
	s_cselect_b32 s0, s53, s55
	s_cselect_b32 s12, s52, s54
	s_lshl_b32 s57, s13, 8
	s_or_b32 s88, s57, 0x8000
	s_and_b64 s[2:3], s[84:85], exec
	s_cselect_b32 s2, 0, 0xc0
	s_or_b32 s7, s2, s88
	v_cndmask_b32_e64 v174, v99, v95, s[84:85]
	v_add_u32_e32 v10, s7, v174
	v_mov_b64_e32 v[12:13], s[22:23]
	v_mad_i64_i32 v[12:13], s[2:3], v10, s14, v[12:13]
	v_lshlrev_b32_e32 v110, 1, v94
	v_mov_b32_e32 v111, v1
	v_lshl_add_u64 v[12:13], s[34:35], 1, v[12:13]
	v_lshl_add_u64 v[12:13], v[12:13], 0, v[110:111]
	v_add_co_u32_e32 v16, vcc, s36, v12
	s_mov_b64 s[2:3], 0x1800
	s_nop 0
	v_addc_co_u32_e32 v17, vcc, 0, v13, vcc
	v_cndmask_b32_e64 v175, v120, v161, s[84:85]
	v_writelane_b32 v255, s37, 6
	v_lshl_add_u64 v[14:15], v[12:13], 0, s[2:3]
	global_load_dwordx4 v[70:73], v[16:17], off offset:2048
	global_load_dwordx4 v[74:77], v[14:15], off offset:16
	global_load_dwordx4 v[78:81], v[12:13], off offset:1040
	global_load_dwordx4 v[82:85], v[12:13], off offset:1024
	v_or_b32_e32 v12, s7, v175
	s_lshl_b32 s30, s37, 8
	v_writelane_b32 v255, s8, 7
	v_ashrrev_i32_e32 v11, 31, v10
	v_mul_u32_u24_e32 v12, 0x3400, v12
	v_mov_b32_e32 v13, v1
	s_ashr_i32 s31, s30, 31
	v_readlane_b32 s36, v255, 0
	v_lshl_add_u64 v[12:13], s[22:23], 0, v[12:13]
	s_lshl_b64 s[2:3], s[30:31], 1
	v_lshlrev_b64 v[10:11], 7, v[10:11]
	v_readlane_b32 s37, v255, 1
	v_lshl_add_u64 v[12:13], v[12:13], 0, s[2:3]
	s_lshl_b32 s10, s8, 8
	s_mov_b32 s11, s94
	v_lshl_add_u64 v[10:11], s[36:37], 0, v[10:11]
	s_lshl_b32 s36, s6, 6
	s_mov_b32 s37, s94
	v_lshl_add_u64 v[12:13], v[12:13], 0, s[10:11]
	v_lshl_add_u64 v[10:11], v[10:11], 0, s[36:37]
	v_mov_b32_e32 v107, v1
	v_lshl_add_u64 v[12:13], v[12:13], 0, v[104:105]
	v_lshl_add_u64 v[10:11], v[10:11], 0, v[106:107]
	global_load_dwordx4 v[86:89], v[12:13], off offset:2048
	global_load_dwordx4 v[90:93], v[12:13], off offset:2064
	global_load_dwordx2 v[118:119], v[10:11], off
	s_and_b64 s[6:7], s[84:85], exec
	s_movk_i32 s6, 0xfc00
	s_cselect_b32 s9, 0, -1
	s_cselect_b32 s8, 0x400, s6
	s_add_u32 s6, s12, s2
	s_addc_u32 s0, s0, s3
	s_add_u32 s6, s6, s10
	s_addc_u32 s0, s0, 0
	v_readlane_b32 s7, v255, 5
	s_add_u32 s6, s6, s7
	s_addc_u32 s7, s0, 0
	v_mov_b32_e32 v109, v1
	v_lshl_add_u64 v[112:113], s[6:7], 0, v[108:109]
	s_lshl_b32 s6, s13, 12
	s_add_u32 s0, s22, s2
	s_addc_u32 s3, s23, s3
	s_add_u32 s2, s0, s10
	s_waitcnt vmcnt(14)
	v_cvt_pk_f16_f32 v66, v2, v3
	s_addc_u32 s3, s3, 0
	v_mov_b32_e32 v2, 0
	s_mov_b64 s[58:59], s[18:19]
	s_mov_b64 s[18:19], s[20:21]
	s_mov_b64 s[20:21], s[78:79]
	v_readlane_b32 s78, v254, 60
	s_movk_i32 s1, 0x3400
	s_waitcnt vmcnt(8)
	v_cvt_pk_f16_f32 v69, v8, v9
	v_cvt_pk_f16_f32 v68, v6, v7
	v_cvt_pk_f16_f32 v67, v4, v5
	v_cndmask_b32_e64 v107, v127, v126, s[84:85]
	v_writelane_b32 v255, s13, 8
	v_lshl_add_u64 v[114:115], v[96:97], 0, s[36:37]
	v_lshl_add_u64 v[116:117], s[2:3], 0, v[104:105]
	s_lshl_b64 s[10:11], s[8:9], 1
	s_mul_hi_i32 s87, s8, 10
	s_mul_i32 s86, s8, 10
	s_movk_i32 s37, 0x42
	s_mov_b32 s7, -4
	v_mov_b32_e32 v3, v2
	v_mov_b32_e32 v4, v2
	v_mov_b32_e32 v5, v2
	v_mov_b32_e32 v6, v2
	v_mov_b32_e32 v7, v2
	v_mov_b32_e32 v8, v2
	v_mov_b32_e32 v9, v2
	v_mov_b32_e32 v10, v2
	v_mov_b32_e32 v11, v2
	v_mov_b32_e32 v12, v2
	v_mov_b32_e32 v13, v2
	v_mov_b32_e32 v14, v2
	v_mov_b32_e32 v15, v2
	v_mov_b32_e32 v16, v2
	v_mov_b32_e32 v17, v2
	v_mov_b32_e32 v18, v2
	v_mov_b32_e32 v19, v2
	v_mov_b32_e32 v20, v2
	v_mov_b32_e32 v21, v2
	v_mov_b32_e32 v22, v2
	v_mov_b32_e32 v23, v2
	v_mov_b32_e32 v24, v2
	v_mov_b32_e32 v25, v2
	v_mov_b32_e32 v26, v2
	v_mov_b32_e32 v27, v2
	v_mov_b32_e32 v28, v2
	v_mov_b32_e32 v29, v2
	v_mov_b32_e32 v30, v2
	v_mov_b32_e32 v31, v2
	v_mov_b32_e32 v32, v2
	v_mov_b32_e32 v33, v2
	s_mov_b32 s56, s17
	v_readlane_b32 s79, v254, 61
	s_waitcnt vmcnt(0)
	v_cvt_pk_f16_f32 v192, v118, v119
	v_cvt_f32_f16_sdwa v34, v86 dst_sel:DWORD dst_unused:UNUSED_PAD src0_sel:WORD_1
	v_cvt_f32_f16_e32 v35, v86
	v_cvt_f32_f16_e32 v36, v90
	v_cvt_pk_bf16_f32 v184, v35, v34
	v_cvt_f32_f16_sdwa v35, v90 dst_sel:DWORD dst_unused:UNUSED_PAD src0_sel:WORD_1
	v_cvt_pk_bf16_f32 v185, v36, v35
	v_cvt_f32_f16_sdwa v34, v87 dst_sel:DWORD dst_unused:UNUSED_PAD src0_sel:WORD_1
	v_cvt_f32_f16_e32 v35, v87
	v_cvt_f32_f16_e32 v36, v91
	v_cvt_pk_bf16_f32 v186, v35, v34
	v_cvt_f32_f16_sdwa v35, v91 dst_sel:DWORD dst_unused:UNUSED_PAD src0_sel:WORD_1
	v_cvt_pk_bf16_f32 v187, v36, v35
	v_cvt_f32_f16_sdwa v34, v88 dst_sel:DWORD dst_unused:UNUSED_PAD src0_sel:WORD_1
	v_cvt_f32_f16_e32 v35, v88
	v_cvt_f32_f16_e32 v36, v92
	v_cvt_pk_bf16_f32 v188, v35, v34
	v_cvt_f32_f16_sdwa v35, v92 dst_sel:DWORD dst_unused:UNUSED_PAD src0_sel:WORD_1
	v_cvt_pk_bf16_f32 v189, v36, v35
	v_cvt_f32_f16_sdwa v34, v89 dst_sel:DWORD dst_unused:UNUSED_PAD src0_sel:WORD_1
	v_cvt_f32_f16_e32 v35, v89
	v_cvt_f32_f16_e32 v36, v93
	v_cvt_pk_bf16_f32 v190, v35, v34
	v_cvt_f32_f16_sdwa v35, v93 dst_sel:DWORD dst_unused:UNUSED_PAD src0_sel:WORD_1
	v_cvt_pk_bf16_f32 v191, v36, v35
	s_branch .LBB0_644
; #define LAS __attribute__((address_space(3)))
; __device__ __forceinline__ void phase_gla(const Frame& F, int l, int gi, int ng, bool last, unsigned* cw) {
;     ...
;             { const f16x8 va = __builtin_bit_cast(f16x8, pv0), vb = __builtin_bit_cast(f16x8, pv1);
; #pragma unroll
;               for (int e = 0; e < 8; e += 2) { const unsigned pa = pk_bf16((float)va[e], (float)va[e + 1]), pb = pk_bf16((float)vb[e], (float)vb[e + 1]);
;                   *(LAS unsigned short*)(lds + GL_VT + ((vs * 16 + e) * 72 + vi) * 2) = (unsigned short)(pa & 0xffffu);
;                   *(LAS unsigned short*)(lds + GL_VT + ((vs * 16 + e + 1) * 72 + vi) * 2) = (unsigned short)(pa >> 16);
;                   *(LAS unsigned short*)(lds + GL_VT + ((vs * 16 + 8 + e) * 72 + vi) * 2) = (unsigned short)(pb & 0xffffu);
;                   *(LAS unsigned short*)(lds + GL_VT + ((vs * 16 + 8 + e + 1) * 72 + vi) * 2) = (unsigned short)(pb >> 16); } }
;     ...
;             { const int cb = chunk_base(s), i0 = it * 32 + 4 * hh; const long rs = dir ? -(long)DM : (long)DM;
;               f16* ob = Oout + (size_t)(cb + (dir ? 63 - i0 : i0)) * DM + h * 256 + sl * 128 + et * 32 + r32;
; #pragma unroll
;               for (int e = 0; e < 16; ++e) ob[((e & 3) + 8 * (e >> 2)) * rs] = (f16)oacc[e]; }
; #pragma unroll
;             for (int q = 0; q < 2; ++q) {
; #pragma unroll
;                 for (int g4 = 0; g4 < 4; ++g4) { const f32x4 ev = *(const LAS f32x4*)(lds + GL_EB + (dt * 32 + g4 * 8 + hh * 4) * 4);
; #pragma unroll
;                     for (int e = 0; e < 4; ++e) Sacc[q][g4 * 4 + e] *= ev[e]; }
; #pragma unroll
;                 for (int ks = 0; ks < 4; ++ks) {
;                     const s16x8 a = *(const LAS s16x8*)(lds + GL_KT + ((dt * 32 + r32) * 72 + ks * 16 + hh * 8) * 2);
;                     const s16x8 bb = *(const LAS s16x8*)(lds + GL_VT + (((e2 + q) * 32 + r32) * 72 + ks * 16 + hh * 8) * 2);
;                     Sacc[q] = __builtin_amdgcn_mfma_f32_32x32x16_bf16(a, bb, Sacc[q], 0, 0, 0); }
; #pragma unroll
;                 for (int g4 = 0; g4 < 4; ++g4)
;                     *(LAS u32x2*)(lds + GL_ST + (((e2 + q) * 32 + r32) * 136 + dt * 32 + g4 * 8 + hh * 4) * 2) = (u32x2){pk_bf16(Sacc[q][g4 * 4], Sacc[q][g4 * 4 + 1]), pk_bf16(Sacc[q][g4 * 4 + 2], Sacc[q][g4 * 4 + 3])};
;             }
;             __syncthreads();
.LBB0_643:
	s_waitcnt lgkmcnt(7)
	v_pk_mul_f32 v[2:3], v[2:3], v[230:231]
	v_pk_mul_f32 v[4:5], v[4:5], v[232:233]
	v_pk_mul_f32 v[18:19], v[18:19], v[230:231]
	v_pk_mul_f32 v[20:21], v[20:21], v[232:233]
	s_waitcnt lgkmcnt(6)
	v_pk_mul_f32 v[6:7], v[6:7], v[242:243]
	v_pk_mul_f32 v[8:9], v[8:9], v[244:245]
	v_pk_mul_f32 v[22:23], v[22:23], v[242:243]
	v_pk_mul_f32 v[24:25], v[24:25], v[244:245]
	s_waitcnt lgkmcnt(5)
	v_pk_mul_f32 v[10:11], v[10:11], v[246:247]
	v_pk_mul_f32 v[12:13], v[12:13], v[248:249]
	v_pk_mul_f32 v[26:27], v[26:27], v[246:247]
	v_pk_mul_f32 v[28:29], v[28:29], v[248:249]
	s_waitcnt lgkmcnt(4)
	v_pk_mul_f32 v[14:15], v[14:15], v[62:63]
	v_pk_mul_f32 v[16:17], v[16:17], v[64:65]
	v_pk_mul_f32 v[30:31], v[30:31], v[62:63]
	v_pk_mul_f32 v[32:33], v[32:33], v[64:65]
	v_add_u32_e32 v184, s0, v107
	v_readlane_b32 s0, v254, 16
	v_ashrrev_i32_e32 v185, 31, v184
	v_lshlrev_b64 v[184:185], 11, v[184:185]
	v_lshl_add_u64 v[184:185], v[112:113], 0, v[184:185]
	v_add_u32_e32 v189, s0, v130
	v_readlane_b32 s0, v254, 17
	ds_read_b128 v[192:195], v189
	ds_read_b128 v[200:203], v173
	ds_read_b128 v[214:217], v189 offset:32
	ds_read_b128 v[218:221], v173 offset:32
	ds_read_b128 v[222:225], v189 offset:64
	ds_read_b128 v[226:229], v173 offset:64
	ds_read_b128 v[230:233], v189 offset:96
	ds_read_b128 v[242:245], v173 offset:96
	v_cvt_f16_f32_e32 v188, v34
	global_store_short v[184:185], v188, off
	v_lshl_add_u64 v[186:187], s[8:9], 1, v[184:185]
	v_cvt_f16_f32_e32 v190, v35
	global_store_short v[186:187], v190, off
	v_lshl_add_u64 v[186:187], v[186:187], 0, s[10:11]
	v_cvt_f16_f32_e32 v188, v36
	global_store_short v[186:187], v188, off
	v_lshl_add_u64 v[186:187], v[186:187], 0, s[10:11]
	v_cvt_f16_f32_e32 v190, v37
	global_store_short v[186:187], v190, off
	v_lshl_add_u64 v[186:187], v[186:187], 0, s[86:87]
	s_waitcnt lgkmcnt(7)
	v_mfma_f32_32x32x16_bf16 v[2:17], v[50:53], v[192:195], v[2:17]
	v_cvt_f16_f32_e32 v188, v38
	global_store_short v[186:187], v188, off
	v_lshl_add_u64 v[186:187], v[186:187], 0, s[10:11]
	v_cvt_f16_f32_e32 v190, v39
	global_store_short v[186:187], v190, off
	s_waitcnt lgkmcnt(6)
	v_mfma_f32_32x32x16_bf16 v[18:33], v[50:53], v[200:203], v[18:33]
	v_lshl_add_u64 v[186:187], v[186:187], 0, s[10:11]
	v_cvt_f16_f32_e32 v188, v40
	global_store_short v[186:187], v188, off
	v_lshl_add_u64 v[186:187], v[186:187], 0, s[10:11]
	v_cvt_f16_f32_e32 v190, v41
	s_waitcnt lgkmcnt(5)
	v_mfma_f32_32x32x16_bf16 v[2:17], v[54:57], v[214:217], v[2:17]
	global_store_short v[186:187], v190, off
	v_lshl_add_u64 v[186:187], v[186:187], 0, s[86:87]
	v_cvt_f16_f32_e32 v188, v42
	global_store_short v[186:187], v188, off
	v_lshl_add_u64 v[186:187], v[186:187], 0, s[10:11]
	s_waitcnt lgkmcnt(4)
	v_mfma_f32_32x32x16_bf16 v[18:33], v[54:57], v[218:221], v[18:33]
	v_cvt_f16_f32_e32 v190, v43
	global_store_short v[186:187], v190, off
	v_lshl_add_u64 v[186:187], v[186:187], 0, s[10:11]
	v_cvt_f16_f32_e32 v188, v44
	global_store_short v[186:187], v188, off
	s_waitcnt lgkmcnt(3)
	v_mfma_f32_32x32x16_bf16 v[2:17], v[58:61], v[222:225], v[2:17]
	v_lshl_add_u64 v[186:187], v[186:187], 0, s[10:11]
	v_cvt_f16_f32_e32 v190, v45
	global_store_short v[186:187], v190, off
	v_lshl_add_u64 v[186:187], v[186:187], 0, s[86:87]
	v_cvt_f16_f32_e32 v188, v46
	s_waitcnt lgkmcnt(2)
	v_mfma_f32_32x32x16_bf16 v[18:33], v[58:61], v[226:229], v[18:33]
	global_store_short v[186:187], v188, off
	v_lshl_add_u64 v[186:187], v[186:187], 0, s[10:11]
	v_cvt_f16_f32_e32 v190, v47
	global_store_short v[186:187], v190, off
	v_lshl_add_u64 v[186:187], v[186:187], 0, s[10:11]
	s_waitcnt lgkmcnt(1)
	v_mfma_f32_32x32x16_bf16 v[2:17], v[180:183], v[230:233], v[2:17]
	v_cvt_f16_f32_e32 v188, v48
	global_store_short v[186:187], v188, off
	v_lshl_add_u64 v[186:187], v[186:187], 0, s[10:11]
	v_cvt_f16_f32_e32 v190, v49
	global_store_short v[186:187], v190, off
	s_waitcnt lgkmcnt(0)
	v_mfma_f32_32x32x16_bf16 v[18:33], v[180:183], v[242:245], v[18:33]
	v_add_u32_e32 v36, s33, v131
	s_nop 10
	v_cvt_pk_bf16_f32 v34, v2, v3
	v_cvt_pk_bf16_f32 v35, v4, v5
	ds_write_b64 v36, v[34:35]
	v_cvt_pk_bf16_f32 v34, v6, v7
	v_cvt_pk_bf16_f32 v35, v8, v9
	v_add_u32_e32 v36, s0, v131
	ds_write_b64 v36, v[34:35]
	v_cvt_pk_bf16_f32 v34, v10, v11
	v_cvt_pk_bf16_f32 v35, v12, v13
	v_add_u32_e32 v36, s95, v131
	ds_write_b64 v36, v[34:35]
	v_cvt_pk_bf16_f32 v34, v14, v15
	v_cvt_pk_bf16_f32 v35, v16, v17
	v_add_u32_e32 v36, s89, v131
	ds_write_b64 v36, v[34:35]
	v_add_u32_e32 v36, s33, v132
	v_cvt_pk_bf16_f32 v34, v18, v19
	v_cvt_pk_bf16_f32 v35, v20, v21
	ds_write_b64 v36, v[34:35]
	v_cvt_pk_bf16_f32 v34, v22, v23
	v_cvt_pk_bf16_f32 v35, v24, v25
	v_add_u32_e32 v36, s0, v132
	ds_write_b64 v36, v[34:35]
	v_cvt_pk_bf16_f32 v34, v26, v27
	v_cvt_pk_bf16_f32 v35, v28, v29
	v_add_u32_e32 v36, s95, v132
	ds_write_b64 v36, v[34:35]
	v_cvt_pk_bf16_f32 v34, v30, v31
	v_cvt_pk_bf16_f32 v35, v32, v33
	v_add_u32_e32 v36, s89, v132
	ds_write_b64 v36, v[34:35]
	s_waitcnt vmcnt(16)
	v_cvt_pk_f16_f32 v192, v118, v119
	v_cvt_f32_f16_sdwa v34, v86 dst_sel:DWORD dst_unused:UNUSED_PAD src0_sel:WORD_1
	v_cvt_f32_f16_e32 v35, v86
	v_cvt_f32_f16_e32 v36, v90
	v_cvt_pk_bf16_f32 v184, v35, v34
	v_cvt_f32_f16_sdwa v35, v90 dst_sel:DWORD dst_unused:UNUSED_PAD src0_sel:WORD_1
	v_cvt_pk_bf16_f32 v185, v36, v35
	v_cvt_f32_f16_sdwa v34, v87 dst_sel:DWORD dst_unused:UNUSED_PAD src0_sel:WORD_1
	v_cvt_f32_f16_e32 v35, v87
	v_cvt_f32_f16_e32 v36, v91
	v_cvt_pk_bf16_f32 v186, v35, v34
	v_cvt_f32_f16_sdwa v35, v91 dst_sel:DWORD dst_unused:UNUSED_PAD src0_sel:WORD_1
	v_cvt_pk_bf16_f32 v187, v36, v35
	v_cvt_f32_f16_sdwa v34, v88 dst_sel:DWORD dst_unused:UNUSED_PAD src0_sel:WORD_1
	v_cvt_f32_f16_e32 v35, v88
	v_cvt_f32_f16_e32 v36, v92
	v_cvt_pk_bf16_f32 v188, v35, v34
	v_cvt_f32_f16_sdwa v35, v92 dst_sel:DWORD dst_unused:UNUSED_PAD src0_sel:WORD_1
	v_cvt_pk_bf16_f32 v189, v36, v35
	v_cvt_f32_f16_sdwa v34, v89 dst_sel:DWORD dst_unused:UNUSED_PAD src0_sel:WORD_1
	v_cvt_f32_f16_e32 v35, v89
	v_cvt_f32_f16_e32 v36, v93
	v_cvt_pk_bf16_f32 v190, v35, v34
	v_cvt_f32_f16_sdwa v35, v93 dst_sel:DWORD dst_unused:UNUSED_PAD src0_sel:WORD_1
	v_cvt_pk_bf16_f32 v191, v36, v35
	s_add_i32 s37, s37, -1
	s_add_i32 s7, s7, 1
	s_cmp_eq_u32 s7, 64
	s_waitcnt lgkmcnt(0)
	s_barrier
	s_cbranch_scc1 .LBB0_666
	.p2align	6
; #define LAS __attribute__((address_space(3)))
; __device__ __forceinline__ unsigned pk_bf16(float lo, float hi) { f32x2 v; v.x = lo; v.y = hi; const bf16x2_t b = __builtin_convertvector(v, bf16x2_t); return __builtin_bit_cast(unsigned, b); }
; __device__ __forceinline__ void phase_gla(const Frame& F, int l, int gi, int ng, bool last, unsigned* cw) {
;     ...
;             *(LAS u32x4*)(lds + GL_RQ + (li * 136 + ls * 16) * 2) = pq0; *(LAS u32x4*)(lds + GL_RQ + (li * 136 + ls * 16 + 8) * 2) = pq1;
;             *(LAS u32x4*)(lds + GL_RK + (li * 136 + ls * 16) * 2) = pk0; *(LAS u32x4*)(lds + GL_RK + (li * 136 + ls * 16 + 8) * 2) = pk1;
;             *(LAS unsigned*)(lds + GL_LR + (li * 16 + ls * 2) * 2) = pk_f16(pg.x, pg.y);
;             { const f16x8 va = __builtin_bit_cast(f16x8, pv0), vb = __builtin_bit_cast(f16x8, pv1);
; #pragma unroll
;               for (int e = 0; e < 8; e += 2) { const unsigned pa = pk_bf16((float)va[e], (float)va[e + 1]), pb = pk_bf16((float)vb[e], (float)vb[e + 1]);
;                   *(LAS unsigned short*)(lds + GL_VT + ((vs * 16 + e) * 72 + vi) * 2) = (unsigned short)(pa & 0xffffu);
;                   *(LAS unsigned short*)(lds + GL_VT + ((vs * 16 + e + 1) * 72 + vi) * 2) = (unsigned short)(pa >> 16);
;                   *(LAS unsigned short*)(lds + GL_VT + ((vs * 16 + 8 + e) * 72 + vi) * 2) = (unsigned short)(pb & 0xffffu);
;                   *(LAS unsigned short*)(lds + GL_VT + ((vs * 16 + 8 + e + 1) * 72 + vi) * 2) = (unsigned short)(pb >> 16); } }
;             __syncthreads();
;             if (s + 1 < 68) GLA_LOAD(s + 1);
;             { const f16x8 ga = *(const LAS f16x8*)(lds + GL_LR + ((w >> 2) * 32 + r32) * 32 + hh * 16);
;               f32x16 la;
; #pragma unroll
;               for (int e = 0; e < 16; ++e) la[e] = 0.f;
;               la = __builtin_amdgcn_mfma_f32_32x32x16_f16(ga, gwf, la, 0, 0, 0);
.LBB0_644:
	ds_write_b128 v137, v[70:73]
	ds_write_b128 v137, v[74:77] offset:16
	ds_write_b128 v137, v[82:85] offset:17408
	ds_write_b128 v137, v[78:81] offset:17424
	ds_write_b32 v138, v192 offset:34816
	s_add_i32 s14, s7, 4
	s_cmp_eq_u32 s7, 63
	ds_write_b16 v139, v184
	ds_write_b16_d16_hi v140, v184
	ds_write_b16 v141, v185
	ds_write_b16_d16_hi v142, v185
	ds_write_b16 v143, v186
	ds_write_b16_d16_hi v144, v186
	ds_write_b16 v145, v187
	ds_write_b16_d16_hi v146, v187
	ds_write_b16 v147, v188
	ds_write_b16_d16_hi v148, v188
	ds_write_b16 v149, v189
	ds_write_b16_d16_hi v150, v189
	ds_write_b16 v151, v190
	ds_write_b16_d16_hi v152, v190
	ds_write_b16 v153, v191
	ds_write_b16_d16_hi v154, v191
	s_waitcnt lgkmcnt(0)
	s_barrier
	ds_read_b128 v[34:37], v155 offset:34816
	s_waitcnt lgkmcnt(0)
	v_mfma_f32_32x32x16_f16 v[34:49], v[34:37], v[66:69], 0
	s_cbranch_scc1 .Lgla_s1_skip
	s_cmp_gt_u32 s14, 2
	s_cselect_b64 s[2:3], -1, 0
	s_mov_b64 s[12:13], -1
	s_and_b64 vcc, exec, s[2:3]
	s_cbranch_vccz .LBB0_647
	s_add_i32 s0, s7, 1
	s_and_b64 s[12:13], s[84:85], exec
	s_cselect_b32 s0, s0, s37
	s_mov_b64 s[12:13], 0
